# SwiGLU activation stores without the nt hint (act stays cacheable for the FFN-down A reads)
# speedup vs baseline: 1.0244x; 1.0011x over previous
.Lg131_nox:
	v_lshl_add_u32 v153, s51, 10, v147
	ds_read2_b32 v[154:155], v153 offset1:16
	v_lshl_or_b32 v156, s52, 7, v148
	v_lshl_add_u32 v152, s18, 8, v144
	s_and_b64 vcc, exec, s[4:5]
	s_mov_b32 s52, s10
	s_waitcnt lgkmcnt(0)
	v_pk_mul_f32 v[124:125], v[124:125], v[154:155] op_sel_hi:[1,0]
	v_pk_mul_f32 v[126:127], v[126:127], v[154:155] op_sel_hi:[1,0]
	v_mul_f32_e32 v157, 0xbfb8aa3b, v124
	v_mul_f32_e32 v158, 0xbfb8aa3b, v125
	v_exp_f32_e32 v159, v157
	v_exp_f32_e32 v158, v158
	v_pk_mul_f32 v[116:117], v[116:117], v[154:155] op_sel_hi:[1,0]
	v_pk_mul_f32 v[120:121], v[120:121], v[154:155] op_sel_hi:[1,0]
	v_add_f32_e32 v159, 1.0, v159
	v_add_f32_e32 v160, 1.0, v158
	v_rcp_f32_e32 v158, v159
	v_mul_f32_e32 v159, 0xbfb8aa3b, v126
	v_exp_f32_e32 v161, v159
	v_mul_f32_e32 v159, 0xbfb8aa3b, v127
	v_exp_f32_e32 v162, v159
	v_rcp_f32_e32 v159, v160
	v_add_f32_e32 v160, 1.0, v161
	v_rcp_f32_e32 v160, v160
	v_add_f32_e32 v161, 1.0, v162
	v_rcp_f32_e32 v161, v161
	v_pk_mul_f32 v[124:125], v[124:125], v[158:159]
	v_pk_mul_f32 v[118:119], v[118:119], v[154:155] op_sel_hi:[1,0]
	v_pk_mul_f32 v[116:117], v[116:117], v[124:125]
	v_pk_mul_f32 v[124:125], v[126:127], v[160:161]
	v_mul_f32_e32 v126, 0xbfb8aa3b, v120
	v_exp_f32_e32 v126, v126
	v_pk_mul_f32 v[118:119], v[118:119], v[124:125]
	v_mul_f32_e32 v124, 0xbfb8aa3b, v121
	v_pk_mul_f32 v[122:123], v[122:123], v[154:155] op_sel_hi:[1,0]
	v_exp_f32_e32 v125, v124
	v_add_f32_e32 v124, 1.0, v126
	v_mul_f32_e32 v126, 0xbfb8aa3b, v122
	v_mul_f32_e32 v127, 0xbfb8aa3b, v123
	v_exp_f32_e32 v126, v126
	v_exp_f32_e32 v127, v127
	v_add_f32_e32 v125, 1.0, v125
	v_rcp_f32_e32 v124, v124
	v_rcp_f32_e32 v125, v125
	v_add_f32_e32 v126, 1.0, v126
	v_add_f32_e32 v127, 1.0, v127
	v_rcp_f32_e32 v126, v126
	v_rcp_f32_e32 v127, v127
	v_pk_mul_f32 v[112:113], v[112:113], v[154:155] op_sel_hi:[1,0]
	v_pk_mul_f32 v[120:121], v[120:121], v[124:125]
	v_pk_mul_f32 v[114:115], v[114:115], v[154:155] op_sel_hi:[1,0]
	v_pk_mul_f32 v[112:113], v[112:113], v[120:121]
	v_pk_mul_f32 v[120:121], v[122:123], v[126:127]
	v_mov_b32_e32 v122, v155
	v_pk_mul_f32 v[108:109], v[108:109], v[122:123] op_sel_hi:[1,0]
	v_ashrrev_i32_e32 v157, 31, v156
	v_mul_f32_e32 v123, 0xbfb8aa3b, v108
	v_exp_f32_e32 v123, v123
	v_pk_mul_f32 v[114:115], v[114:115], v[120:121]
	v_cvt_pk_bf16_f32 v116, v116, v117
	v_cvt_pk_bf16_f32 v117, v118, v119
	v_cvt_pk_bf16_f32 v118, v112, v113
	v_mov_b64_e32 v[112:113], s[6:7]
	v_cvt_pk_bf16_f32 v119, v114, v115
	v_mad_i64_i32 v[120:121], s[20:21], v152, s49, v[112:113]
	v_lshlrev_b64 v[114:115], 1, v[156:157]
	v_lshl_add_u64 v[120:121], v[120:121], 0, v[114:115]
	global_store_dwordx4 v[120:121], v[116:119], off
	v_pk_mul_f32 v[110:111], v[110:111], v[122:123] op_sel_hi:[1,0]
	v_pk_mul_f32 v[100:101], v[100:101], v[122:123] op_sel_hi:[1,0]
	v_mul_f32_e32 v116, 0xbfb8aa3b, v109
	v_exp_f32_e32 v117, v116
	v_mul_f32_e32 v118, 0xbfb8aa3b, v110
	v_mul_f32_e32 v119, 0xbfb8aa3b, v111
	v_exp_f32_e32 v118, v118
	v_exp_f32_e32 v119, v119
	v_add_f32_e32 v116, 1.0, v123
	v_add_f32_e32 v117, 1.0, v117
	v_rcp_f32_e32 v116, v116
	v_rcp_f32_e32 v117, v117
	v_add_f32_e32 v118, 1.0, v118
	v_add_f32_e32 v119, 1.0, v119
	v_rcp_f32_e32 v118, v118
	v_rcp_f32_e32 v119, v119
	v_pk_mul_f32 v[108:109], v[108:109], v[116:117]
	v_pk_mul_f32 v[104:105], v[104:105], v[122:123] op_sel_hi:[1,0]
	v_pk_mul_f32 v[100:101], v[100:101], v[108:109]
	v_pk_mul_f32 v[108:109], v[110:111], v[118:119]
	v_mul_f32_e32 v110, 0xbfb8aa3b, v104
	v_exp_f32_e32 v110, v110
	v_pk_mul_f32 v[102:103], v[102:103], v[122:123] op_sel_hi:[1,0]
	v_pk_mul_f32 v[106:107], v[106:107], v[122:123] op_sel_hi:[1,0]
	v_pk_mul_f32 v[102:103], v[102:103], v[108:109]
	v_mul_f32_e32 v108, 0xbfb8aa3b, v105
	v_exp_f32_e32 v109, v108
	v_add_f32_e32 v108, 1.0, v110
	v_mul_f32_e32 v110, 0xbfb8aa3b, v106
	v_mul_f32_e32 v111, 0xbfb8aa3b, v107
	v_exp_f32_e32 v110, v110
	v_exp_f32_e32 v111, v111
	v_add_f32_e32 v109, 1.0, v109
	v_rcp_f32_e32 v108, v108
	v_rcp_f32_e32 v109, v109
	v_add_f32_e32 v110, 1.0, v110
	v_add_f32_e32 v111, 1.0, v111
	v_rcp_f32_e32 v110, v110
	v_rcp_f32_e32 v111, v111
	v_pk_mul_f32 v[96:97], v[96:97], v[122:123] op_sel_hi:[1,0]
	v_pk_mul_f32 v[104:105], v[104:105], v[108:109]
	v_or_b32_e32 v108, 16, v152
	v_pk_mul_f32 v[104:105], v[96:97], v[104:105]
	v_pk_mul_f32 v[96:97], v[98:99], v[122:123] op_sel_hi:[1,0]
	v_pk_mul_f32 v[98:99], v[106:107], v[110:111]
	s_mov_b32 s18, s12
	v_pk_mul_f32 v[106:107], v[96:97], v[98:99]
	v_cvt_pk_bf16_f32 v96, v100, v101
	ds_read2_b32 v[100:101], v153 offset0:32 offset1:48
	v_cvt_pk_bf16_f32 v97, v102, v103
	v_mad_i64_i32 v[102:103], s[20:21], v108, s49, v[112:113]
	v_cvt_pk_bf16_f32 v98, v104, v105
	v_cvt_pk_bf16_f32 v99, v106, v107
	v_lshl_add_u64 v[102:103], v[102:103], 0, v[114:115]
	s_waitcnt lgkmcnt(0)
	v_pk_mul_f32 v[92:93], v[92:93], v[100:101] op_sel_hi:[1,0]
	global_store_dwordx4 v[102:103], v[96:99], off
	v_mul_f32_e32 v104, 0xbfb8aa3b, v92
	v_pk_mul_f32 v[94:95], v[94:95], v[100:101] op_sel_hi:[1,0]
	v_mul_f32_e32 v96, 0xbfb8aa3b, v93
	v_exp_f32_e32 v104, v104
	v_exp_f32_e32 v97, v96
	v_mul_f32_e32 v98, 0xbfb8aa3b, v94
	v_mul_f32_e32 v99, 0xbfb8aa3b, v95
	v_exp_f32_e32 v98, v98
	v_exp_f32_e32 v99, v99
	v_add_f32_e32 v96, 1.0, v104
	v_add_f32_e32 v97, 1.0, v97
	v_rcp_f32_e32 v96, v96
	v_rcp_f32_e32 v97, v97
	v_add_f32_e32 v98, 1.0, v98
	v_add_f32_e32 v99, 1.0, v99
	v_rcp_f32_e32 v98, v98
	v_rcp_f32_e32 v99, v99
	v_pk_mul_f32 v[84:85], v[84:85], v[100:101] op_sel_hi:[1,0]
	v_pk_mul_f32 v[92:93], v[92:93], v[96:97]
	v_pk_mul_f32 v[88:89], v[88:89], v[100:101] op_sel_hi:[1,0]
	v_pk_mul_f32 v[84:85], v[84:85], v[92:93]
	v_pk_mul_f32 v[92:93], v[94:95], v[98:99]
	v_mul_f32_e32 v94, 0xbfb8aa3b, v88
	v_exp_f32_e32 v94, v94
	v_pk_mul_f32 v[86:87], v[86:87], v[100:101] op_sel_hi:[1,0]
	v_pk_mul_f32 v[90:91], v[90:91], v[100:101] op_sel_hi:[1,0]
	v_pk_mul_f32 v[86:87], v[86:87], v[92:93]
	v_mul_f32_e32 v92, 0xbfb8aa3b, v89
	v_exp_f32_e32 v93, v92
	v_add_f32_e32 v92, 1.0, v94
	v_mul_f32_e32 v94, 0xbfb8aa3b, v90
	v_mul_f32_e32 v95, 0xbfb8aa3b, v91
	v_exp_f32_e32 v94, v94
	v_exp_f32_e32 v95, v95
	v_add_f32_e32 v93, 1.0, v93
	v_rcp_f32_e32 v92, v92
	v_rcp_f32_e32 v93, v93
	v_add_f32_e32 v94, 1.0, v94
	v_add_f32_e32 v95, 1.0, v95
	v_rcp_f32_e32 v94, v94
	v_rcp_f32_e32 v95, v95
	v_pk_mul_f32 v[80:81], v[80:81], v[100:101] op_sel_hi:[1,0]
	v_pk_mul_f32 v[88:89], v[88:89], v[92:93]
	v_or_b32_e32 v92, 32, v152
	v_pk_mul_f32 v[88:89], v[80:81], v[88:89]
	v_pk_mul_f32 v[80:81], v[82:83], v[100:101] op_sel_hi:[1,0]
	v_pk_mul_f32 v[82:83], v[90:91], v[94:95]
	s_mov_b64 s[26:27], s[16:17]
	v_pk_mul_f32 v[90:91], v[80:81], v[82:83]
	v_cvt_pk_bf16_f32 v81, v86, v87
	v_mov_b32_e32 v86, v101
	v_pk_mul_f32 v[76:77], v[76:77], v[86:87] op_sel_hi:[1,0]
	v_cvt_pk_bf16_f32 v80, v84, v85
	v_mul_f32_e32 v87, 0xbfb8aa3b, v76
	v_exp_f32_e32 v87, v87
	v_mad_i64_i32 v[84:85], s[20:21], v92, s49, v[112:113]
	v_cvt_pk_bf16_f32 v82, v88, v89
	v_cvt_pk_bf16_f32 v83, v90, v91
	v_lshl_add_u64 v[84:85], v[84:85], 0, v[114:115]
	global_store_dwordx4 v[84:85], v[80:83], off
	v_pk_mul_f32 v[78:79], v[78:79], v[86:87] op_sel_hi:[1,0]
	v_pk_mul_f32 v[68:69], v[68:69], v[86:87] op_sel_hi:[1,0]
	v_mul_f32_e32 v80, 0xbfb8aa3b, v77
	v_exp_f32_e32 v81, v80
	v_mul_f32_e32 v82, 0xbfb8aa3b, v78
	v_mul_f32_e32 v83, 0xbfb8aa3b, v79
	v_exp_f32_e32 v82, v82
	v_exp_f32_e32 v83, v83
	v_add_f32_e32 v80, 1.0, v87
	v_add_f32_e32 v81, 1.0, v81
	v_rcp_f32_e32 v80, v80
	v_rcp_f32_e32 v81, v81
	v_add_f32_e32 v82, 1.0, v82
	v_add_f32_e32 v83, 1.0, v83
	v_rcp_f32_e32 v82, v82
	v_rcp_f32_e32 v83, v83
	v_pk_mul_f32 v[76:77], v[76:77], v[80:81]
	v_pk_mul_f32 v[72:73], v[72:73], v[86:87] op_sel_hi:[1,0]
	v_pk_mul_f32 v[68:69], v[68:69], v[76:77]
	v_pk_mul_f32 v[76:77], v[78:79], v[82:83]
	v_mul_f32_e32 v78, 0xbfb8aa3b, v72
	v_exp_f32_e32 v78, v78
	v_pk_mul_f32 v[70:71], v[70:71], v[86:87] op_sel_hi:[1,0]
	v_pk_mul_f32 v[74:75], v[74:75], v[86:87] op_sel_hi:[1,0]
	v_pk_mul_f32 v[70:71], v[70:71], v[76:77]
	v_mul_f32_e32 v76, 0xbfb8aa3b, v73
	v_exp_f32_e32 v77, v76
	v_add_f32_e32 v76, 1.0, v78
	v_mul_f32_e32 v78, 0xbfb8aa3b, v74
	v_mul_f32_e32 v79, 0xbfb8aa3b, v75
	v_exp_f32_e32 v78, v78
	v_exp_f32_e32 v79, v79
	v_add_f32_e32 v77, 1.0, v77
	v_rcp_f32_e32 v76, v76
	v_rcp_f32_e32 v77, v77
	v_add_f32_e32 v78, 1.0, v78
	v_add_f32_e32 v79, 1.0, v79
	v_rcp_f32_e32 v78, v78
	v_rcp_f32_e32 v79, v79
	v_pk_mul_f32 v[64:65], v[64:65], v[86:87] op_sel_hi:[1,0]
	v_pk_mul_f32 v[72:73], v[72:73], v[76:77]
	v_or_b32_e32 v76, 48, v152
	v_pk_mul_f32 v[72:73], v[64:65], v[72:73]
	v_pk_mul_f32 v[64:65], v[66:67], v[86:87] op_sel_hi:[1,0]
	v_pk_mul_f32 v[66:67], v[74:75], v[78:79]
	s_mov_b32 s51, s50
	v_pk_mul_f32 v[74:75], v[64:65], v[66:67]
	v_cvt_pk_bf16_f32 v64, v68, v69
	ds_read2_b32 v[68:69], v153 offset0:128 offset1:144
	v_cvt_pk_bf16_f32 v65, v70, v71
	v_mad_i64_i32 v[70:71], s[20:21], v76, s49, v[112:113]
	v_cvt_pk_bf16_f32 v66, v72, v73
	v_cvt_pk_bf16_f32 v67, v74, v75
	v_lshl_add_u64 v[70:71], v[70:71], 0, v[114:115]
	s_waitcnt lgkmcnt(0)
	v_pk_mul_f32 v[60:61], v[60:61], v[68:69] op_sel_hi:[1,0]
	global_store_dwordx4 v[70:71], v[64:67], off
	v_pk_mul_f32 v[62:63], v[62:63], v[68:69] op_sel_hi:[1,0]
	v_pk_mul_f32 v[52:53], v[52:53], v[68:69] op_sel_hi:[1,0]
	v_mul_f32_e32 v64, 0xbfb8aa3b, v60
	v_mul_f32_e32 v65, 0xbfb8aa3b, v61
	v_exp_f32_e32 v64, v64
	v_exp_f32_e32 v65, v65
	v_mul_f32_e32 v66, 0xbfb8aa3b, v62
	v_mul_f32_e32 v67, 0xbfb8aa3b, v63
	v_exp_f32_e32 v66, v66
	v_exp_f32_e32 v67, v67
	v_add_f32_e32 v64, 1.0, v64
	v_add_f32_e32 v65, 1.0, v65
	v_rcp_f32_e32 v64, v64
	v_rcp_f32_e32 v65, v65
	v_add_f32_e32 v66, 1.0, v66
	v_add_f32_e32 v67, 1.0, v67
	v_rcp_f32_e32 v66, v66
	v_rcp_f32_e32 v67, v67
	v_pk_mul_f32 v[60:61], v[60:61], v[64:65]
	v_pk_mul_f32 v[56:57], v[56:57], v[68:69] op_sel_hi:[1,0]
	v_pk_mul_f32 v[52:53], v[52:53], v[60:61]
	v_pk_mul_f32 v[60:61], v[62:63], v[66:67]
	v_mul_f32_e32 v62, 0xbfb8aa3b, v56
	v_exp_f32_e32 v62, v62
	v_pk_mul_f32 v[54:55], v[54:55], v[68:69] op_sel_hi:[1,0]
	v_pk_mul_f32 v[58:59], v[58:59], v[68:69] op_sel_hi:[1,0]
	v_pk_mul_f32 v[54:55], v[54:55], v[60:61]
	v_mul_f32_e32 v60, 0xbfb8aa3b, v57
	v_exp_f32_e32 v61, v60
	v_add_f32_e32 v60, 1.0, v62
	v_mul_f32_e32 v62, 0xbfb8aa3b, v58
	v_mul_f32_e32 v63, 0xbfb8aa3b, v59
	v_exp_f32_e32 v62, v62
	v_exp_f32_e32 v63, v63
	v_add_f32_e32 v61, 1.0, v61
	v_rcp_f32_e32 v60, v60
	v_rcp_f32_e32 v61, v61
	v_add_f32_e32 v62, 1.0, v62
	v_add_f32_e32 v63, 1.0, v63
	v_rcp_f32_e32 v62, v62
	v_rcp_f32_e32 v63, v63
	v_pk_mul_f32 v[48:49], v[48:49], v[68:69] op_sel_hi:[1,0]
	v_pk_mul_f32 v[56:57], v[56:57], v[60:61]
	v_add_u32_e32 v70, 0x80, v152
	v_pk_mul_f32 v[56:57], v[48:49], v[56:57]
	v_pk_mul_f32 v[48:49], v[50:51], v[68:69] op_sel_hi:[1,0]
	v_pk_mul_f32 v[50:51], v[58:59], v[62:63]
	s_nop 0
	v_pk_mul_f32 v[58:59], v[48:49], v[50:51]
	v_cvt_pk_bf16_f32 v49, v54, v55
	v_mov_b32_e32 v54, v69
	v_pk_mul_f32 v[44:45], v[44:45], v[54:55] op_sel_hi:[1,0]
	v_cvt_pk_bf16_f32 v48, v52, v53
	v_mul_f32_e32 v55, 0xbfb8aa3b, v44
	v_exp_f32_e32 v55, v55
	v_mad_i64_i32 v[52:53], s[20:21], v70, s49, v[112:113]
	v_cvt_pk_bf16_f32 v50, v56, v57
	v_cvt_pk_bf16_f32 v51, v58, v59
	v_lshl_add_u64 v[52:53], v[52:53], 0, v[114:115]
	global_store_dwordx4 v[52:53], v[48:51], off
	v_pk_mul_f32 v[46:47], v[46:47], v[54:55] op_sel_hi:[1,0]
	v_pk_mul_f32 v[36:37], v[36:37], v[54:55] op_sel_hi:[1,0]
	v_mul_f32_e32 v48, 0xbfb8aa3b, v45
	v_exp_f32_e32 v49, v48
	v_mul_f32_e32 v50, 0xbfb8aa3b, v46
	v_mul_f32_e32 v51, 0xbfb8aa3b, v47
	v_exp_f32_e32 v50, v50
	v_exp_f32_e32 v51, v51
	v_add_f32_e32 v48, 1.0, v55
	v_add_f32_e32 v49, 1.0, v49
	v_rcp_f32_e32 v48, v48
	v_rcp_f32_e32 v49, v49
	v_add_f32_e32 v50, 1.0, v50
	v_add_f32_e32 v51, 1.0, v51
	v_rcp_f32_e32 v50, v50
	v_rcp_f32_e32 v51, v51
	v_pk_mul_f32 v[44:45], v[44:45], v[48:49]
	v_pk_mul_f32 v[40:41], v[40:41], v[54:55] op_sel_hi:[1,0]
	v_pk_mul_f32 v[36:37], v[36:37], v[44:45]
	v_pk_mul_f32 v[44:45], v[46:47], v[50:51]
	v_mul_f32_e32 v46, 0xbfb8aa3b, v40
	v_exp_f32_e32 v46, v46
	v_pk_mul_f32 v[38:39], v[38:39], v[54:55] op_sel_hi:[1,0]
	v_pk_mul_f32 v[42:43], v[42:43], v[54:55] op_sel_hi:[1,0]
	v_pk_mul_f32 v[38:39], v[38:39], v[44:45]
	v_mul_f32_e32 v44, 0xbfb8aa3b, v41
	v_exp_f32_e32 v45, v44
	v_add_f32_e32 v44, 1.0, v46
	v_mul_f32_e32 v46, 0xbfb8aa3b, v42
	v_mul_f32_e32 v47, 0xbfb8aa3b, v43
	v_exp_f32_e32 v46, v46
	v_exp_f32_e32 v47, v47
	v_add_f32_e32 v45, 1.0, v45
	v_rcp_f32_e32 v44, v44
	v_rcp_f32_e32 v45, v45
	v_add_f32_e32 v46, 1.0, v46
	v_add_f32_e32 v47, 1.0, v47
	v_rcp_f32_e32 v46, v46
	v_rcp_f32_e32 v47, v47
	v_pk_mul_f32 v[32:33], v[32:33], v[54:55] op_sel_hi:[1,0]
	v_pk_mul_f32 v[40:41], v[40:41], v[44:45]
	v_add_u32_e32 v44, 0x90, v152
	v_pk_mul_f32 v[40:41], v[32:33], v[40:41]
	v_pk_mul_f32 v[32:33], v[34:35], v[54:55] op_sel_hi:[1,0]
	v_pk_mul_f32 v[34:35], v[42:43], v[46:47]
	s_nop 0
	v_pk_mul_f32 v[42:43], v[32:33], v[34:35]
	v_cvt_pk_bf16_f32 v32, v36, v37
	ds_read2_b32 v[36:37], v153 offset0:160 offset1:176
	v_cvt_pk_bf16_f32 v33, v38, v39
	v_mad_i64_i32 v[38:39], s[20:21], v44, s49, v[112:113]
	v_cvt_pk_bf16_f32 v34, v40, v41
	v_cvt_pk_bf16_f32 v35, v42, v43
	v_lshl_add_u64 v[38:39], v[38:39], 0, v[114:115]
	s_waitcnt lgkmcnt(0)
	v_pk_mul_f32 v[28:29], v[28:29], v[36:37] op_sel_hi:[1,0]
	global_store_dwordx4 v[38:39], v[32:35], off
	v_mul_f32_e32 v40, 0xbfb8aa3b, v28
	v_pk_mul_f32 v[30:31], v[30:31], v[36:37] op_sel_hi:[1,0]
	v_mul_f32_e32 v32, 0xbfb8aa3b, v29
	v_exp_f32_e32 v40, v40
	v_exp_f32_e32 v33, v32
	v_mul_f32_e32 v34, 0xbfb8aa3b, v30
	v_mul_f32_e32 v35, 0xbfb8aa3b, v31
	v_exp_f32_e32 v34, v34
	v_exp_f32_e32 v35, v35
	v_add_f32_e32 v32, 1.0, v40
	v_add_f32_e32 v33, 1.0, v33
	v_rcp_f32_e32 v32, v32
	v_rcp_f32_e32 v33, v33
	v_add_f32_e32 v34, 1.0, v34
	v_add_f32_e32 v35, 1.0, v35
	v_rcp_f32_e32 v34, v34
	v_rcp_f32_e32 v35, v35
	v_pk_mul_f32 v[20:21], v[20:21], v[36:37] op_sel_hi:[1,0]
	v_pk_mul_f32 v[28:29], v[28:29], v[32:33]
	v_pk_mul_f32 v[24:25], v[24:25], v[36:37] op_sel_hi:[1,0]
	v_pk_mul_f32 v[20:21], v[20:21], v[28:29]
	v_pk_mul_f32 v[28:29], v[30:31], v[34:35]
	v_mul_f32_e32 v30, 0xbfb8aa3b, v24
	v_exp_f32_e32 v30, v30
	v_pk_mul_f32 v[22:23], v[22:23], v[36:37] op_sel_hi:[1,0]
	v_pk_mul_f32 v[26:27], v[26:27], v[36:37] op_sel_hi:[1,0]
	v_pk_mul_f32 v[22:23], v[22:23], v[28:29]
	v_mul_f32_e32 v28, 0xbfb8aa3b, v25
	v_exp_f32_e32 v29, v28
	v_add_f32_e32 v28, 1.0, v30
	v_mul_f32_e32 v30, 0xbfb8aa3b, v26
	v_mul_f32_e32 v31, 0xbfb8aa3b, v27
	v_exp_f32_e32 v30, v30
	v_exp_f32_e32 v31, v31
	v_add_f32_e32 v29, 1.0, v29
	v_rcp_f32_e32 v28, v28
	v_rcp_f32_e32 v29, v29
	v_add_f32_e32 v30, 1.0, v30
	v_add_f32_e32 v31, 1.0, v31
	v_rcp_f32_e32 v30, v30
	v_rcp_f32_e32 v31, v31
	v_pk_mul_f32 v[16:17], v[16:17], v[36:37] op_sel_hi:[1,0]
	v_pk_mul_f32 v[24:25], v[24:25], v[28:29]
	v_add_u32_e32 v28, 0xa0, v152
	v_pk_mul_f32 v[24:25], v[16:17], v[24:25]
	v_pk_mul_f32 v[16:17], v[18:19], v[36:37] op_sel_hi:[1,0]
	v_pk_mul_f32 v[18:19], v[26:27], v[30:31]
	s_nop 0
	v_pk_mul_f32 v[26:27], v[16:17], v[18:19]
	v_cvt_pk_bf16_f32 v17, v22, v23
	v_mov_b32_e32 v22, v37
	v_pk_mul_f32 v[12:13], v[12:13], v[22:23] op_sel_hi:[1,0]
	v_cvt_pk_bf16_f32 v16, v20, v21
	v_mul_f32_e32 v23, 0xbfb8aa3b, v12
	v_exp_f32_e32 v23, v23
	v_mad_i64_i32 v[20:21], s[20:21], v28, s49, v[112:113]
	v_cvt_pk_bf16_f32 v18, v24, v25
	v_cvt_pk_bf16_f32 v19, v26, v27
	v_lshl_add_u64 v[20:21], v[20:21], 0, v[114:115]
	global_store_dwordx4 v[20:21], v[16:19], off
	v_pk_mul_f32 v[14:15], v[14:15], v[22:23] op_sel_hi:[1,0]
	v_pk_mul_f32 v[4:5], v[4:5], v[22:23] op_sel_hi:[1,0]
	v_mul_f32_e32 v16, 0xbfb8aa3b, v13
	v_exp_f32_e32 v17, v16
	v_mul_f32_e32 v18, 0xbfb8aa3b, v14
	v_mul_f32_e32 v19, 0xbfb8aa3b, v15
	v_exp_f32_e32 v18, v18
	v_exp_f32_e32 v19, v19
	v_add_f32_e32 v16, 1.0, v23
	v_add_f32_e32 v17, 1.0, v17
	v_rcp_f32_e32 v16, v16
	v_rcp_f32_e32 v17, v17
	v_add_f32_e32 v18, 1.0, v18
	v_add_f32_e32 v19, 1.0, v19
	v_rcp_f32_e32 v18, v18
	v_rcp_f32_e32 v19, v19
	v_pk_mul_f32 v[12:13], v[12:13], v[16:17]
	v_pk_mul_f32 v[8:9], v[8:9], v[22:23] op_sel_hi:[1,0]
	v_pk_mul_f32 v[4:5], v[4:5], v[12:13]
	v_pk_mul_f32 v[12:13], v[14:15], v[18:19]
	v_mul_f32_e32 v14, 0xbfb8aa3b, v8
	v_exp_f32_e32 v14, v14
	v_pk_mul_f32 v[6:7], v[6:7], v[22:23] op_sel_hi:[1,0]
	v_pk_mul_f32 v[10:11], v[10:11], v[22:23] op_sel_hi:[1,0]
	v_pk_mul_f32 v[6:7], v[6:7], v[12:13]
	v_mul_f32_e32 v12, 0xbfb8aa3b, v9
	v_exp_f32_e32 v13, v12
	v_add_f32_e32 v12, 1.0, v14
	v_mul_f32_e32 v14, 0xbfb8aa3b, v10
	v_mul_f32_e32 v15, 0xbfb8aa3b, v11
	v_exp_f32_e32 v14, v14
	v_exp_f32_e32 v15, v15
	v_add_f32_e32 v13, 1.0, v13
	v_rcp_f32_e32 v12, v12
	v_rcp_f32_e32 v13, v13
	v_add_f32_e32 v14, 1.0, v14
	v_add_f32_e32 v15, 1.0, v15
	v_rcp_f32_e32 v14, v14
	v_rcp_f32_e32 v15, v15
	v_pk_mul_f32 v[0:1], v[0:1], v[22:23] op_sel_hi:[1,0]
	v_pk_mul_f32 v[8:9], v[8:9], v[12:13]
	v_add_u32_e32 v12, 0xb0, v152
	v_pk_mul_f32 v[8:9], v[0:1], v[8:9]
	v_pk_mul_f32 v[0:1], v[2:3], v[22:23] op_sel_hi:[1,0]
	v_pk_mul_f32 v[2:3], v[10:11], v[14:15]
	s_nop 0
	v_pk_mul_f32 v[10:11], v[0:1], v[2:3]
	v_cvt_pk_bf16_f32 v0, v4, v5
	v_mad_i64_i32 v[4:5], s[20:21], v12, s49, v[112:113]
	v_cvt_pk_bf16_f32 v1, v6, v7
	v_cvt_pk_bf16_f32 v2, v8, v9
	v_cvt_pk_bf16_f32 v3, v10, v11
	v_lshl_add_u64 v[4:5], v[4:5], 0, v[114:115]
	s_mov_b64 s[20:21], s[14:15]
	global_store_dwordx4 v[4:5], v[0:3], off
	s_cbranch_vccz .LBB0_128
	s_waitcnt vmcnt(0)
	s_cmpk_gt_u32 s37, 0xff
	s_cbranch_scc1 .LBB0_135

.Lg893_nox:
	v_lshl_add_u32 v152, s51, 10, v146
	ds_read2_b32 v[154:155], v152 offset1:16
	v_lshl_or_b32 v156, s52, 7, v147
	v_lshl_add_u32 v151, s18, 8, v144
	s_and_b64 vcc, exec, s[4:5]
	s_mov_b32 s52, s10
	s_waitcnt lgkmcnt(0)
	v_pk_mul_f32 v[124:125], v[124:125], v[154:155] op_sel_hi:[1,0]
	v_pk_mul_f32 v[126:127], v[126:127], v[154:155] op_sel_hi:[1,0]
	v_mul_f32_e32 v153, 0xbfb8aa3b, v124
	v_mul_f32_e32 v157, 0xbfb8aa3b, v125
	v_exp_f32_e32 v153, v153
	v_exp_f32_e32 v158, v157
	v_mul_f32_e32 v160, 0xbfb8aa3b, v127
	v_exp_f32_e32 v161, v160
	v_add_f32_e32 v153, 1.0, v153
	v_add_f32_e32 v159, 1.0, v158
	v_rcp_f32_e32 v158, v153
	v_mul_f32_e32 v153, 0xbfb8aa3b, v126
	v_exp_f32_e32 v153, v153
	v_rcp_f32_e32 v159, v159
	v_pk_mul_f32 v[116:117], v[116:117], v[154:155] op_sel_hi:[1,0]
	v_pk_mul_f32 v[120:121], v[120:121], v[154:155] op_sel_hi:[1,0]
	v_add_f32_e32 v153, 1.0, v153
	v_rcp_f32_e32 v160, v153
	v_add_f32_e32 v153, 1.0, v161
	v_rcp_f32_e32 v161, v153
	v_pk_mul_f32 v[124:125], v[124:125], v[158:159]
	v_pk_mul_f32 v[118:119], v[118:119], v[154:155] op_sel_hi:[1,0]
	v_pk_mul_f32 v[116:117], v[116:117], v[124:125]
	v_pk_mul_f32 v[124:125], v[126:127], v[160:161]
	v_mul_f32_e32 v126, 0xbfb8aa3b, v120
	v_exp_f32_e32 v126, v126
	v_pk_mul_f32 v[118:119], v[118:119], v[124:125]
	v_mul_f32_e32 v124, 0xbfb8aa3b, v121
	v_pk_mul_f32 v[122:123], v[122:123], v[154:155] op_sel_hi:[1,0]
	v_exp_f32_e32 v125, v124
	v_add_f32_e32 v124, 1.0, v126
	v_mul_f32_e32 v126, 0xbfb8aa3b, v122
	v_mul_f32_e32 v127, 0xbfb8aa3b, v123
	v_exp_f32_e32 v126, v126
	v_exp_f32_e32 v127, v127
	v_add_f32_e32 v125, 1.0, v125
	v_rcp_f32_e32 v124, v124
	v_rcp_f32_e32 v125, v125
	v_add_f32_e32 v126, 1.0, v126
	v_add_f32_e32 v127, 1.0, v127
	v_rcp_f32_e32 v126, v126
	v_rcp_f32_e32 v127, v127
	v_pk_mul_f32 v[112:113], v[112:113], v[154:155] op_sel_hi:[1,0]
	v_pk_mul_f32 v[120:121], v[120:121], v[124:125]
	v_pk_mul_f32 v[114:115], v[114:115], v[154:155] op_sel_hi:[1,0]
	v_pk_mul_f32 v[112:113], v[112:113], v[120:121]
	v_pk_mul_f32 v[120:121], v[122:123], v[126:127]
	v_mov_b32_e32 v122, v155
	v_pk_mul_f32 v[108:109], v[108:109], v[122:123] op_sel_hi:[1,0]
	v_ashrrev_i32_e32 v157, 31, v156
	v_mul_f32_e32 v123, 0xbfb8aa3b, v108
	v_exp_f32_e32 v123, v123
	v_pk_mul_f32 v[114:115], v[114:115], v[120:121]
	v_cvt_pk_bf16_f32 v116, v116, v117
	v_cvt_pk_bf16_f32 v117, v118, v119
	v_cvt_pk_bf16_f32 v118, v112, v113
	v_mov_b64_e32 v[112:113], s[6:7]
	v_cvt_pk_bf16_f32 v119, v114, v115
	v_mad_i64_i32 v[120:121], s[20:21], v151, s49, v[112:113]
	v_lshlrev_b64 v[114:115], 1, v[156:157]
	v_lshl_add_u64 v[120:121], v[120:121], 0, v[114:115]
	global_store_dwordx4 v[120:121], v[116:119], off
	v_pk_mul_f32 v[110:111], v[110:111], v[122:123] op_sel_hi:[1,0]
	v_pk_mul_f32 v[100:101], v[100:101], v[122:123] op_sel_hi:[1,0]
	v_mul_f32_e32 v116, 0xbfb8aa3b, v109
	v_exp_f32_e32 v117, v116
	v_mul_f32_e32 v118, 0xbfb8aa3b, v110
	v_mul_f32_e32 v119, 0xbfb8aa3b, v111
	v_exp_f32_e32 v118, v118
	v_exp_f32_e32 v119, v119
	v_add_f32_e32 v116, 1.0, v123
	v_add_f32_e32 v117, 1.0, v117
	v_rcp_f32_e32 v116, v116
	v_rcp_f32_e32 v117, v117
	v_add_f32_e32 v118, 1.0, v118
	v_add_f32_e32 v119, 1.0, v119
	v_rcp_f32_e32 v118, v118
	v_rcp_f32_e32 v119, v119
	v_pk_mul_f32 v[108:109], v[108:109], v[116:117]
	v_pk_mul_f32 v[104:105], v[104:105], v[122:123] op_sel_hi:[1,0]
	v_pk_mul_f32 v[100:101], v[100:101], v[108:109]
	v_pk_mul_f32 v[108:109], v[110:111], v[118:119]
	v_mul_f32_e32 v110, 0xbfb8aa3b, v104
	v_exp_f32_e32 v110, v110
	v_pk_mul_f32 v[102:103], v[102:103], v[122:123] op_sel_hi:[1,0]
	v_pk_mul_f32 v[106:107], v[106:107], v[122:123] op_sel_hi:[1,0]
	v_pk_mul_f32 v[102:103], v[102:103], v[108:109]
	v_mul_f32_e32 v108, 0xbfb8aa3b, v105
	v_exp_f32_e32 v109, v108
	v_add_f32_e32 v108, 1.0, v110
	v_mul_f32_e32 v110, 0xbfb8aa3b, v106
	v_mul_f32_e32 v111, 0xbfb8aa3b, v107
	v_exp_f32_e32 v110, v110
	v_exp_f32_e32 v111, v111
	v_add_f32_e32 v109, 1.0, v109
	v_rcp_f32_e32 v108, v108
	v_rcp_f32_e32 v109, v109
	v_add_f32_e32 v110, 1.0, v110
	v_add_f32_e32 v111, 1.0, v111
	v_rcp_f32_e32 v110, v110
	v_rcp_f32_e32 v111, v111
	v_pk_mul_f32 v[96:97], v[96:97], v[122:123] op_sel_hi:[1,0]
	v_pk_mul_f32 v[104:105], v[104:105], v[108:109]
	v_or_b32_e32 v108, 16, v151
	v_pk_mul_f32 v[104:105], v[96:97], v[104:105]
	v_pk_mul_f32 v[96:97], v[98:99], v[122:123] op_sel_hi:[1,0]
	v_pk_mul_f32 v[98:99], v[106:107], v[110:111]
	s_mov_b32 s18, s12
	v_pk_mul_f32 v[106:107], v[96:97], v[98:99]
	v_cvt_pk_bf16_f32 v96, v100, v101
	ds_read2_b32 v[100:101], v152 offset0:32 offset1:48
	v_cvt_pk_bf16_f32 v97, v102, v103
	v_mad_i64_i32 v[102:103], s[20:21], v108, s49, v[112:113]
	v_cvt_pk_bf16_f32 v98, v104, v105
	v_cvt_pk_bf16_f32 v99, v106, v107
	v_lshl_add_u64 v[102:103], v[102:103], 0, v[114:115]
	s_waitcnt lgkmcnt(0)
	v_pk_mul_f32 v[92:93], v[92:93], v[100:101] op_sel_hi:[1,0]
	global_store_dwordx4 v[102:103], v[96:99], off
	v_mul_f32_e32 v104, 0xbfb8aa3b, v92
	v_pk_mul_f32 v[94:95], v[94:95], v[100:101] op_sel_hi:[1,0]
	v_mul_f32_e32 v96, 0xbfb8aa3b, v93
	v_exp_f32_e32 v104, v104
	v_exp_f32_e32 v97, v96
	v_mul_f32_e32 v98, 0xbfb8aa3b, v94
	v_mul_f32_e32 v99, 0xbfb8aa3b, v95
	v_exp_f32_e32 v98, v98
	v_exp_f32_e32 v99, v99
	v_add_f32_e32 v96, 1.0, v104
	v_add_f32_e32 v97, 1.0, v97
	v_rcp_f32_e32 v96, v96
	v_rcp_f32_e32 v97, v97
	v_add_f32_e32 v98, 1.0, v98
	v_add_f32_e32 v99, 1.0, v99
	v_rcp_f32_e32 v98, v98
	v_rcp_f32_e32 v99, v99
	v_pk_mul_f32 v[84:85], v[84:85], v[100:101] op_sel_hi:[1,0]
	v_pk_mul_f32 v[92:93], v[92:93], v[96:97]
	v_pk_mul_f32 v[88:89], v[88:89], v[100:101] op_sel_hi:[1,0]
	v_pk_mul_f32 v[84:85], v[84:85], v[92:93]
	v_pk_mul_f32 v[92:93], v[94:95], v[98:99]
	v_mul_f32_e32 v94, 0xbfb8aa3b, v88
	v_exp_f32_e32 v94, v94
	v_pk_mul_f32 v[86:87], v[86:87], v[100:101] op_sel_hi:[1,0]
	v_pk_mul_f32 v[90:91], v[90:91], v[100:101] op_sel_hi:[1,0]
	v_pk_mul_f32 v[86:87], v[86:87], v[92:93]
	v_mul_f32_e32 v92, 0xbfb8aa3b, v89
	v_exp_f32_e32 v93, v92
	v_add_f32_e32 v92, 1.0, v94
	v_mul_f32_e32 v94, 0xbfb8aa3b, v90
	v_mul_f32_e32 v95, 0xbfb8aa3b, v91
	v_exp_f32_e32 v94, v94
	v_exp_f32_e32 v95, v95
	v_add_f32_e32 v93, 1.0, v93
	v_rcp_f32_e32 v92, v92
	v_rcp_f32_e32 v93, v93
	v_add_f32_e32 v94, 1.0, v94
	v_add_f32_e32 v95, 1.0, v95
	v_rcp_f32_e32 v94, v94
	v_rcp_f32_e32 v95, v95
	v_pk_mul_f32 v[80:81], v[80:81], v[100:101] op_sel_hi:[1,0]
	v_pk_mul_f32 v[88:89], v[88:89], v[92:93]
	v_or_b32_e32 v92, 32, v151
	v_pk_mul_f32 v[88:89], v[80:81], v[88:89]
	v_pk_mul_f32 v[80:81], v[82:83], v[100:101] op_sel_hi:[1,0]
	v_pk_mul_f32 v[82:83], v[90:91], v[94:95]
	s_mov_b64 s[26:27], s[16:17]
	v_pk_mul_f32 v[90:91], v[80:81], v[82:83]
	v_cvt_pk_bf16_f32 v81, v86, v87
	v_mov_b32_e32 v86, v101
	v_pk_mul_f32 v[76:77], v[76:77], v[86:87] op_sel_hi:[1,0]
	v_cvt_pk_bf16_f32 v80, v84, v85
	v_mul_f32_e32 v87, 0xbfb8aa3b, v76
	v_exp_f32_e32 v87, v87
	v_mad_i64_i32 v[84:85], s[20:21], v92, s49, v[112:113]
	v_cvt_pk_bf16_f32 v82, v88, v89
	v_cvt_pk_bf16_f32 v83, v90, v91
	v_lshl_add_u64 v[84:85], v[84:85], 0, v[114:115]
	global_store_dwordx4 v[84:85], v[80:83], off
	v_pk_mul_f32 v[78:79], v[78:79], v[86:87] op_sel_hi:[1,0]
	v_pk_mul_f32 v[68:69], v[68:69], v[86:87] op_sel_hi:[1,0]
	v_mul_f32_e32 v80, 0xbfb8aa3b, v77
	v_exp_f32_e32 v81, v80
	v_mul_f32_e32 v82, 0xbfb8aa3b, v78
	v_mul_f32_e32 v83, 0xbfb8aa3b, v79
	v_exp_f32_e32 v82, v82
	v_exp_f32_e32 v83, v83
	v_add_f32_e32 v80, 1.0, v87
	v_add_f32_e32 v81, 1.0, v81
	v_rcp_f32_e32 v80, v80
	v_rcp_f32_e32 v81, v81
	v_add_f32_e32 v82, 1.0, v82
	v_add_f32_e32 v83, 1.0, v83
	v_rcp_f32_e32 v82, v82
	v_rcp_f32_e32 v83, v83
	v_pk_mul_f32 v[76:77], v[76:77], v[80:81]
	v_pk_mul_f32 v[72:73], v[72:73], v[86:87] op_sel_hi:[1,0]
	v_pk_mul_f32 v[68:69], v[68:69], v[76:77]
	v_pk_mul_f32 v[76:77], v[78:79], v[82:83]
	v_mul_f32_e32 v78, 0xbfb8aa3b, v72
	v_exp_f32_e32 v78, v78
	v_pk_mul_f32 v[70:71], v[70:71], v[86:87] op_sel_hi:[1,0]
	v_pk_mul_f32 v[74:75], v[74:75], v[86:87] op_sel_hi:[1,0]
	v_pk_mul_f32 v[70:71], v[70:71], v[76:77]
	v_mul_f32_e32 v76, 0xbfb8aa3b, v73
	v_exp_f32_e32 v77, v76
	v_add_f32_e32 v76, 1.0, v78
	v_mul_f32_e32 v78, 0xbfb8aa3b, v74
	v_mul_f32_e32 v79, 0xbfb8aa3b, v75
	v_exp_f32_e32 v78, v78
	v_exp_f32_e32 v79, v79
	v_add_f32_e32 v77, 1.0, v77
	v_rcp_f32_e32 v76, v76
	v_rcp_f32_e32 v77, v77
	v_add_f32_e32 v78, 1.0, v78
	v_add_f32_e32 v79, 1.0, v79
	v_rcp_f32_e32 v78, v78
	v_rcp_f32_e32 v79, v79
	v_pk_mul_f32 v[64:65], v[64:65], v[86:87] op_sel_hi:[1,0]
	v_pk_mul_f32 v[72:73], v[72:73], v[76:77]
	v_or_b32_e32 v76, 48, v151
	v_pk_mul_f32 v[72:73], v[64:65], v[72:73]
	v_pk_mul_f32 v[64:65], v[66:67], v[86:87] op_sel_hi:[1,0]
	v_pk_mul_f32 v[66:67], v[74:75], v[78:79]
	s_mov_b32 s51, s50
	v_pk_mul_f32 v[74:75], v[64:65], v[66:67]
	v_cvt_pk_bf16_f32 v64, v68, v69
	ds_read2_b32 v[68:69], v152 offset0:128 offset1:144
	v_cvt_pk_bf16_f32 v65, v70, v71
	v_mad_i64_i32 v[70:71], s[20:21], v76, s49, v[112:113]
	v_cvt_pk_bf16_f32 v66, v72, v73
	v_cvt_pk_bf16_f32 v67, v74, v75
	v_lshl_add_u64 v[70:71], v[70:71], 0, v[114:115]
	s_waitcnt lgkmcnt(0)
	v_pk_mul_f32 v[60:61], v[60:61], v[68:69] op_sel_hi:[1,0]
	global_store_dwordx4 v[70:71], v[64:67], off
	v_pk_mul_f32 v[62:63], v[62:63], v[68:69] op_sel_hi:[1,0]
	v_pk_mul_f32 v[52:53], v[52:53], v[68:69] op_sel_hi:[1,0]
	v_mul_f32_e32 v64, 0xbfb8aa3b, v60
	v_mul_f32_e32 v65, 0xbfb8aa3b, v61
	v_exp_f32_e32 v64, v64
	v_exp_f32_e32 v65, v65
	v_mul_f32_e32 v66, 0xbfb8aa3b, v62
	v_mul_f32_e32 v67, 0xbfb8aa3b, v63
	v_exp_f32_e32 v66, v66
	v_exp_f32_e32 v67, v67
	v_add_f32_e32 v64, 1.0, v64
	v_add_f32_e32 v65, 1.0, v65
	v_rcp_f32_e32 v64, v64
	v_rcp_f32_e32 v65, v65
	v_add_f32_e32 v66, 1.0, v66
	v_add_f32_e32 v67, 1.0, v67
	v_rcp_f32_e32 v66, v66
	v_rcp_f32_e32 v67, v67
	v_pk_mul_f32 v[60:61], v[60:61], v[64:65]
	v_pk_mul_f32 v[56:57], v[56:57], v[68:69] op_sel_hi:[1,0]
	v_pk_mul_f32 v[52:53], v[52:53], v[60:61]
	v_pk_mul_f32 v[60:61], v[62:63], v[66:67]
	v_mul_f32_e32 v62, 0xbfb8aa3b, v56
	v_exp_f32_e32 v62, v62
	v_pk_mul_f32 v[54:55], v[54:55], v[68:69] op_sel_hi:[1,0]
	v_pk_mul_f32 v[58:59], v[58:59], v[68:69] op_sel_hi:[1,0]
	v_pk_mul_f32 v[54:55], v[54:55], v[60:61]
	v_mul_f32_e32 v60, 0xbfb8aa3b, v57
	v_exp_f32_e32 v61, v60
	v_add_f32_e32 v60, 1.0, v62
	v_mul_f32_e32 v62, 0xbfb8aa3b, v58
	v_mul_f32_e32 v63, 0xbfb8aa3b, v59
	v_exp_f32_e32 v62, v62
	v_exp_f32_e32 v63, v63
	v_add_f32_e32 v61, 1.0, v61
	v_rcp_f32_e32 v60, v60
	v_rcp_f32_e32 v61, v61
	v_add_f32_e32 v62, 1.0, v62
	v_add_f32_e32 v63, 1.0, v63
	v_rcp_f32_e32 v62, v62
	v_rcp_f32_e32 v63, v63
	v_pk_mul_f32 v[48:49], v[48:49], v[68:69] op_sel_hi:[1,0]
	v_pk_mul_f32 v[56:57], v[56:57], v[60:61]
	v_add_u32_e32 v70, 0x80, v151
	v_pk_mul_f32 v[56:57], v[48:49], v[56:57]
	v_pk_mul_f32 v[48:49], v[50:51], v[68:69] op_sel_hi:[1,0]
	v_pk_mul_f32 v[50:51], v[58:59], v[62:63]
	s_nop 0
	v_pk_mul_f32 v[58:59], v[48:49], v[50:51]
	v_cvt_pk_bf16_f32 v49, v54, v55
	v_mov_b32_e32 v54, v69
	v_pk_mul_f32 v[44:45], v[44:45], v[54:55] op_sel_hi:[1,0]
	v_cvt_pk_bf16_f32 v48, v52, v53
	v_mul_f32_e32 v55, 0xbfb8aa3b, v44
	v_exp_f32_e32 v55, v55
	v_mad_i64_i32 v[52:53], s[20:21], v70, s49, v[112:113]
	v_cvt_pk_bf16_f32 v50, v56, v57
	v_cvt_pk_bf16_f32 v51, v58, v59
	v_lshl_add_u64 v[52:53], v[52:53], 0, v[114:115]
	global_store_dwordx4 v[52:53], v[48:51], off
	v_pk_mul_f32 v[46:47], v[46:47], v[54:55] op_sel_hi:[1,0]
	v_pk_mul_f32 v[36:37], v[36:37], v[54:55] op_sel_hi:[1,0]
	v_mul_f32_e32 v48, 0xbfb8aa3b, v45
	v_exp_f32_e32 v49, v48
	v_mul_f32_e32 v50, 0xbfb8aa3b, v46
	v_mul_f32_e32 v51, 0xbfb8aa3b, v47
	v_exp_f32_e32 v50, v50
	v_exp_f32_e32 v51, v51
	v_add_f32_e32 v48, 1.0, v55
	v_add_f32_e32 v49, 1.0, v49
	v_rcp_f32_e32 v48, v48
	v_rcp_f32_e32 v49, v49
	v_add_f32_e32 v50, 1.0, v50
	v_add_f32_e32 v51, 1.0, v51
	v_rcp_f32_e32 v50, v50
	v_rcp_f32_e32 v51, v51
	v_pk_mul_f32 v[44:45], v[44:45], v[48:49]
	v_pk_mul_f32 v[40:41], v[40:41], v[54:55] op_sel_hi:[1,0]
	v_pk_mul_f32 v[36:37], v[36:37], v[44:45]
	v_pk_mul_f32 v[44:45], v[46:47], v[50:51]
	v_mul_f32_e32 v46, 0xbfb8aa3b, v40
	v_exp_f32_e32 v46, v46
	v_pk_mul_f32 v[38:39], v[38:39], v[54:55] op_sel_hi:[1,0]
	v_pk_mul_f32 v[42:43], v[42:43], v[54:55] op_sel_hi:[1,0]
	v_pk_mul_f32 v[38:39], v[38:39], v[44:45]
	v_mul_f32_e32 v44, 0xbfb8aa3b, v41
	v_exp_f32_e32 v45, v44
	v_add_f32_e32 v44, 1.0, v46
	v_mul_f32_e32 v46, 0xbfb8aa3b, v42
	v_mul_f32_e32 v47, 0xbfb8aa3b, v43
	v_exp_f32_e32 v46, v46
	v_exp_f32_e32 v47, v47
	v_add_f32_e32 v45, 1.0, v45
	v_rcp_f32_e32 v44, v44
	v_rcp_f32_e32 v45, v45
	v_add_f32_e32 v46, 1.0, v46
	v_add_f32_e32 v47, 1.0, v47
	v_rcp_f32_e32 v46, v46
	v_rcp_f32_e32 v47, v47
	v_pk_mul_f32 v[32:33], v[32:33], v[54:55] op_sel_hi:[1,0]
	v_pk_mul_f32 v[40:41], v[40:41], v[44:45]
	v_add_u32_e32 v44, 0x90, v151
	v_pk_mul_f32 v[40:41], v[32:33], v[40:41]
	v_pk_mul_f32 v[32:33], v[34:35], v[54:55] op_sel_hi:[1,0]
	v_pk_mul_f32 v[34:35], v[42:43], v[46:47]
	s_nop 0
	v_pk_mul_f32 v[42:43], v[32:33], v[34:35]
	v_cvt_pk_bf16_f32 v32, v36, v37
	ds_read2_b32 v[36:37], v152 offset0:160 offset1:176
	v_cvt_pk_bf16_f32 v33, v38, v39
	v_mad_i64_i32 v[38:39], s[20:21], v44, s49, v[112:113]
	v_cvt_pk_bf16_f32 v34, v40, v41
	v_cvt_pk_bf16_f32 v35, v42, v43
	v_lshl_add_u64 v[38:39], v[38:39], 0, v[114:115]
	s_waitcnt lgkmcnt(0)
	v_pk_mul_f32 v[28:29], v[28:29], v[36:37] op_sel_hi:[1,0]
	global_store_dwordx4 v[38:39], v[32:35], off
	v_mul_f32_e32 v40, 0xbfb8aa3b, v28
	v_pk_mul_f32 v[30:31], v[30:31], v[36:37] op_sel_hi:[1,0]
	v_mul_f32_e32 v32, 0xbfb8aa3b, v29
	v_exp_f32_e32 v40, v40
	v_exp_f32_e32 v33, v32
	v_mul_f32_e32 v34, 0xbfb8aa3b, v30
	v_mul_f32_e32 v35, 0xbfb8aa3b, v31
	v_exp_f32_e32 v34, v34
	v_exp_f32_e32 v35, v35
	v_add_f32_e32 v32, 1.0, v40
	v_add_f32_e32 v33, 1.0, v33
	v_rcp_f32_e32 v32, v32
	v_rcp_f32_e32 v33, v33
	v_add_f32_e32 v34, 1.0, v34
	v_add_f32_e32 v35, 1.0, v35
	v_rcp_f32_e32 v34, v34
	v_rcp_f32_e32 v35, v35
	v_pk_mul_f32 v[20:21], v[20:21], v[36:37] op_sel_hi:[1,0]
	v_pk_mul_f32 v[28:29], v[28:29], v[32:33]
	v_pk_mul_f32 v[24:25], v[24:25], v[36:37] op_sel_hi:[1,0]
	v_pk_mul_f32 v[20:21], v[20:21], v[28:29]
	v_pk_mul_f32 v[28:29], v[30:31], v[34:35]
	v_mul_f32_e32 v30, 0xbfb8aa3b, v24
	v_exp_f32_e32 v30, v30
	v_pk_mul_f32 v[22:23], v[22:23], v[36:37] op_sel_hi:[1,0]
	v_pk_mul_f32 v[26:27], v[26:27], v[36:37] op_sel_hi:[1,0]
	v_pk_mul_f32 v[22:23], v[22:23], v[28:29]
	v_mul_f32_e32 v28, 0xbfb8aa3b, v25
	v_exp_f32_e32 v29, v28
	v_add_f32_e32 v28, 1.0, v30
	v_mul_f32_e32 v30, 0xbfb8aa3b, v26
	v_mul_f32_e32 v31, 0xbfb8aa3b, v27
	v_exp_f32_e32 v30, v30
	v_exp_f32_e32 v31, v31
	v_add_f32_e32 v29, 1.0, v29
	v_rcp_f32_e32 v28, v28
	v_rcp_f32_e32 v29, v29
	v_add_f32_e32 v30, 1.0, v30
	v_add_f32_e32 v31, 1.0, v31
	v_rcp_f32_e32 v30, v30
	v_rcp_f32_e32 v31, v31
	v_pk_mul_f32 v[16:17], v[16:17], v[36:37] op_sel_hi:[1,0]
	v_pk_mul_f32 v[24:25], v[24:25], v[28:29]
	v_add_u32_e32 v28, 0xa0, v151
	v_pk_mul_f32 v[24:25], v[16:17], v[24:25]
	v_pk_mul_f32 v[16:17], v[18:19], v[36:37] op_sel_hi:[1,0]
	v_pk_mul_f32 v[18:19], v[26:27], v[30:31]
	s_nop 0
	v_pk_mul_f32 v[26:27], v[16:17], v[18:19]
	v_cvt_pk_bf16_f32 v17, v22, v23
	v_mov_b32_e32 v22, v37
	v_pk_mul_f32 v[12:13], v[12:13], v[22:23] op_sel_hi:[1,0]
	v_cvt_pk_bf16_f32 v16, v20, v21
	v_mul_f32_e32 v23, 0xbfb8aa3b, v12
	v_exp_f32_e32 v23, v23
	v_mad_i64_i32 v[20:21], s[20:21], v28, s49, v[112:113]
	v_cvt_pk_bf16_f32 v18, v24, v25
	v_cvt_pk_bf16_f32 v19, v26, v27
	v_lshl_add_u64 v[20:21], v[20:21], 0, v[114:115]
	global_store_dwordx4 v[20:21], v[16:19], off
	v_pk_mul_f32 v[14:15], v[14:15], v[22:23] op_sel_hi:[1,0]
	v_pk_mul_f32 v[4:5], v[4:5], v[22:23] op_sel_hi:[1,0]
	v_mul_f32_e32 v16, 0xbfb8aa3b, v13
	v_exp_f32_e32 v17, v16
	v_mul_f32_e32 v18, 0xbfb8aa3b, v14
	v_mul_f32_e32 v19, 0xbfb8aa3b, v15
	v_exp_f32_e32 v18, v18
	v_exp_f32_e32 v19, v19
	v_add_f32_e32 v16, 1.0, v23
	v_add_f32_e32 v17, 1.0, v17
	v_rcp_f32_e32 v16, v16
	v_rcp_f32_e32 v17, v17
	v_add_f32_e32 v18, 1.0, v18
	v_add_f32_e32 v19, 1.0, v19
	v_rcp_f32_e32 v18, v18
	v_rcp_f32_e32 v19, v19
	v_pk_mul_f32 v[12:13], v[12:13], v[16:17]
	v_pk_mul_f32 v[8:9], v[8:9], v[22:23] op_sel_hi:[1,0]
	v_pk_mul_f32 v[4:5], v[4:5], v[12:13]
	v_pk_mul_f32 v[12:13], v[14:15], v[18:19]
	v_mul_f32_e32 v14, 0xbfb8aa3b, v8
	v_exp_f32_e32 v14, v14
	v_pk_mul_f32 v[6:7], v[6:7], v[22:23] op_sel_hi:[1,0]
	v_pk_mul_f32 v[10:11], v[10:11], v[22:23] op_sel_hi:[1,0]
	v_pk_mul_f32 v[6:7], v[6:7], v[12:13]
	v_mul_f32_e32 v12, 0xbfb8aa3b, v9
	v_exp_f32_e32 v13, v12
	v_add_f32_e32 v12, 1.0, v14
	v_mul_f32_e32 v14, 0xbfb8aa3b, v10
	v_mul_f32_e32 v15, 0xbfb8aa3b, v11
	v_exp_f32_e32 v14, v14
	v_exp_f32_e32 v15, v15
	v_add_f32_e32 v13, 1.0, v13
	v_rcp_f32_e32 v12, v12
	v_rcp_f32_e32 v13, v13
	v_add_f32_e32 v14, 1.0, v14
	v_add_f32_e32 v15, 1.0, v15
	v_rcp_f32_e32 v14, v14
	v_rcp_f32_e32 v15, v15
	v_pk_mul_f32 v[0:1], v[0:1], v[22:23] op_sel_hi:[1,0]
	v_pk_mul_f32 v[8:9], v[8:9], v[12:13]
	v_add_u32_e32 v12, 0xb0, v151
	v_pk_mul_f32 v[8:9], v[0:1], v[8:9]
	v_pk_mul_f32 v[0:1], v[2:3], v[22:23] op_sel_hi:[1,0]
	v_pk_mul_f32 v[2:3], v[10:11], v[14:15]
	s_nop 0
	v_pk_mul_f32 v[10:11], v[0:1], v[2:3]
	v_cvt_pk_bf16_f32 v0, v4, v5
	v_mad_i64_i32 v[4:5], s[20:21], v12, s49, v[112:113]
	v_cvt_pk_bf16_f32 v1, v6, v7
	v_cvt_pk_bf16_f32 v2, v8, v9
	v_cvt_pk_bf16_f32 v3, v10, v11
	v_lshl_add_u64 v[4:5], v[4:5], 0, v[114:115]
	s_mov_b64 s[20:21], s[14:15]
	global_store_dwordx4 v[4:5], v[0:3], off
	s_cbranch_vccz .LBB0_890
	s_waitcnt vmcnt(0)
	s_cmpk_gt_u32 s30, 0xff
	s_cbranch_scc1 .LBB0_897
